# gate/up GEMM loop: LDS-DMA prefetch loads issued first in every load phase, fragment ds_reads after them
# baseline (speedup 1.0000x reference)
; #define PG8_STAGE(bufoff, gbase, voff) do { _Pragma("unroll") for (int _i = 0; _i < 2; ++_i) \
;         __builtin_amdgcn_global_load_lds((const unsigned*)((const char*)(gbase) + (voff)[_i]), (LAS unsigned*)(lds + (bufoff) + ldsw + _i * 8192), 16, 0, 0); } while (0)
; #define PG8_LDA(dst, b, h) do { _Pragma("unroll") for (int m = 0; m < 4; ++m) _Pragma("unroll") for (int k = 0; k < 2; ++k) dst[m][k] = *(const LAS bf16x8*)(lds + PG8_SA(b, h) + aoff + m * 2048 + k * 1024); } while (0)
; #define PG8_LDB(dst, b, h) do { _Pragma("unroll") for (int n = 0; n < 2; ++n) _Pragma("unroll") for (int k = 0; k < 2; ++k) dst[n][k] = *(const LAS bf16x8*)(lds + PG8_SB(b, h) + boff + n * 2048 + k * 1024); } while (0)
; #define PG8_MMA(ai, bj, At, Bt) do { __builtin_amdgcn_s_setprio(1); _Pragma("unroll") for (int m = 0; m < 4; ++m) _Pragma("unroll") for (int n = 0; n < 2; ++n) _Pragma("unroll") for (int k = 0; k < 2; ++k) \
;         acc[ai][bj][m][n] = __builtin_amdgcn_mfma_f32_16x16x32_bf16(Bt[n][k], At[m][k], acc[ai][bj][m][n], 0, 0, 0); __builtin_amdgcn_s_setprio(0); } while (0)
; #define PG8_WAIT_V(n) asm volatile("s_waitcnt vmcnt(" #n ")" ::: "memory")
; #define PG8_WAIT_L(n) asm volatile("s_waitcnt lgkmcnt(" #n ")" ::: "memory")
; #define PG8_BAR __builtin_amdgcn_s_barrier()
; #define PG8_SCHED __builtin_amdgcn_sched_barrier(0)
; template <class Epi, class Sched, bool ALIGN_EPI>
; DI void gemm_phase(LAS unsigned char* lds, const Gemm g, const Sched& S, const Epi& E) {
;     ...
;             PG8_LDB(B0, 0, 0); PG8_LDB(B1, 0, 1); PG8_SCHED; PG8_LDA(At, 0, 0); PG8_STAGE(PG8_SA(1, 1), a1 + hstep, voffA);
;             PG8_WAIT_V(8); PG8_WAIT_L(0); PG8_BAR; PG8_MMA(0, 0, At, B0); PG8_MMA(0, 1, At, B1); PG8_BAR; PG8_SCHED;
;             PG8_LDA(At, 0, 1); PG8_STAGE(PG8_SB(0, 0), b2, voffA); PG8_STAGE(PG8_SB(0, 1), b2 + hstep, voffA); PG8_STAGE(PG8_SA(0, 0), a2, voffA);
;             PG8_WAIT_V(8); PG8_WAIT_L(0); PG8_BAR; PG8_MMA(1, 0, At, B0); PG8_MMA(1, 1, At, B1); PG8_BAR; PG8_SCHED;
.LBB0_826:
	s_add_u32 s30, s0, 0xfffc0080
	s_addc_u32 s31, s1, -1
	s_add_i32 s46, 0, 0x10000
	s_cmp_eq_u32 s45, 12
	s_cselect_b32 s35, s25, s31
	s_cselect_b32 s34, s24, s30
	s_cselect_b32 s31, s23, s44
	s_cselect_b32 s30, s29, s43
	s_add_i32 s52, 0, 0x14000
	s_add_i32 m0, s93, 0xc000
	s_nop 0
	global_load_lds_dwordx4 v178, s[0:1]
	s_add_i32 m0, s93, 0xe000
	s_nop 0
	global_load_lds_dwordx4 v180, s[0:1]
	ds_read_b128 v[44:47], v206
	ds_read_b128 v[48:51], v206 offset:1024
	ds_read_b128 v[52:55], v206 offset:2048
	ds_read_b128 v[56:59], v206 offset:3072
	ds_read_b128 v[124:127], v206 offset:16384
	ds_read_b128 v[128:131], v206 offset:17408
	ds_read_b128 v[132:135], v206 offset:18432
	ds_read_b128 v[136:139], v206 offset:19456
	ds_read_b128 v[160:163], v245
	ds_read_b128 v[164:167], v245 offset:1024
	ds_read_b128 v[182:185], v245 offset:2048
	ds_read_b128 v[186:189], v245 offset:3072
	ds_read_b128 v[190:193], v245 offset:4096
	ds_read_b128 v[194:197], v245 offset:5120
	ds_read_b128 v[198:201], v245 offset:6144
	ds_read_b128 v[202:205], v245 offset:7168
	s_waitcnt vmcnt(8)
	s_waitcnt lgkmcnt(0)
	s_barrier
	s_waitcnt lgkmcnt(0)
	v_mfma_f32_16x16x32_bf16 v[156:159], v[44:47], v[160:163], v[156:159]
	v_mfma_f32_16x16x32_bf16 v[76:79], v[52:55], v[160:163], v[76:79]
	v_mfma_f32_16x16x32_bf16 v[148:151], v[44:47], v[182:185], v[148:151]
	v_mfma_f32_16x16x32_bf16 v[68:71], v[52:55], v[182:185], v[68:71]
	v_mfma_f32_16x16x32_bf16 v[140:143], v[44:47], v[190:193], v[140:143]
	v_mfma_f32_16x16x32_bf16 v[60:63], v[52:55], v[190:193], v[60:63]
	v_mfma_f32_16x16x32_bf16 v[116:119], v[44:47], v[198:201], v[116:119]
	v_mfma_f32_16x16x32_bf16 v[36:39], v[52:55], v[198:201], v[36:39]
	v_mfma_f32_16x16x32_bf16 v[156:159], v[48:51], v[164:167], v[156:159]
	v_mfma_f32_16x16x32_bf16 v[76:79], v[56:59], v[164:167], v[76:79]
	v_mfma_f32_16x16x32_bf16 v[148:151], v[48:51], v[186:189], v[148:151]
	v_mfma_f32_16x16x32_bf16 v[68:71], v[56:59], v[186:189], v[68:71]
	v_mfma_f32_16x16x32_bf16 v[140:143], v[48:51], v[194:197], v[140:143]
	v_mfma_f32_16x16x32_bf16 v[60:63], v[56:59], v[194:197], v[60:63]
	v_mfma_f32_16x16x32_bf16 v[116:119], v[48:51], v[202:205], v[116:119]
	v_mfma_f32_16x16x32_bf16 v[36:39], v[56:59], v[202:205], v[36:39]
	v_mfma_f32_16x16x32_bf16 v[152:155], v[124:127], v[160:163], v[152:155]
	v_mfma_f32_16x16x32_bf16 v[72:75], v[132:135], v[160:163], v[72:75]
	v_mfma_f32_16x16x32_bf16 v[144:147], v[124:127], v[182:185], v[144:147]
	v_mfma_f32_16x16x32_bf16 v[64:67], v[132:135], v[182:185], v[64:67]
	v_mfma_f32_16x16x32_bf16 v[120:123], v[124:127], v[190:193], v[120:123]
	v_mfma_f32_16x16x32_bf16 v[40:43], v[132:135], v[190:193], v[40:43]
	v_mfma_f32_16x16x32_bf16 v[112:115], v[124:127], v[198:201], v[112:115]
	v_mfma_f32_16x16x32_bf16 v[32:35], v[132:135], v[198:201], v[32:35]
	v_mfma_f32_16x16x32_bf16 v[152:155], v[128:131], v[164:167], v[152:155]
	v_mfma_f32_16x16x32_bf16 v[72:75], v[136:139], v[164:167], v[72:75]
	v_mfma_f32_16x16x32_bf16 v[144:147], v[128:131], v[186:189], v[144:147]
	v_mfma_f32_16x16x32_bf16 v[64:67], v[136:139], v[186:189], v[64:67]
	v_mfma_f32_16x16x32_bf16 v[120:123], v[128:131], v[194:197], v[120:123]
	v_mfma_f32_16x16x32_bf16 v[40:43], v[136:139], v[194:197], v[40:43]
	v_mfma_f32_16x16x32_bf16 v[112:115], v[128:131], v[202:205], v[112:115]
	v_mfma_f32_16x16x32_bf16 v[32:35], v[136:139], v[202:205], v[32:35]
	s_barrier
	s_add_i32 s46, s46, s92
	s_add_u32 s94, s30, s2
	s_addc_u32 s95, s31, s3
	s_add_u32 s96, s34, s2
	s_addc_u32 s97, s35, s3
	s_mov_b32 m0, s46
	s_nop 0
	global_load_lds_dwordx4 v174, s[30:31]
	s_add_i32 m0, s46, 0x2000
	s_add_u32 s46, s30, 0x40000
	s_addc_u32 s47, s31, 0
	s_add_i32 s52, s52, s92
	global_load_lds_dwordx4 v176, s[30:31]
	s_mov_b32 m0, s52
	s_nop 0
	global_load_lds_dwordx4 v174, s[46:47]
	s_add_i32 m0, s52, 0x2000
	s_nop 0
	global_load_lds_dwordx4 v176, s[46:47]
	s_mov_b32 m0, s93
	s_nop 0
	global_load_lds_dwordx4 v174, s[34:35]
	s_mov_b32 m0, s86
	s_nop 0
	global_load_lds_dwordx4 v176, s[34:35]
	ds_read_b128 v[160:163], v245 offset:16384
	ds_read_b128 v[164:167], v245 offset:17408
	ds_read_b128 v[182:185], v245 offset:18432
	ds_read_b128 v[186:189], v245 offset:19456
	ds_read_b128 v[190:193], v245 offset:20480
	ds_read_b128 v[194:197], v245 offset:21504
	ds_read_b128 v[198:201], v245 offset:22528
	ds_read_b128 v[202:205], v245 offset:23552
	s_waitcnt vmcnt(8)
	s_waitcnt lgkmcnt(0)
	s_barrier
	s_waitcnt lgkmcnt(0)
	v_mfma_f32_16x16x32_bf16 v[108:111], v[44:47], v[160:163], v[108:111]
	v_mfma_f32_16x16x32_bf16 v[28:31], v[52:55], v[160:163], v[28:31]
	v_mfma_f32_16x16x32_bf16 v[100:103], v[44:47], v[182:185], v[100:103]
	v_mfma_f32_16x16x32_bf16 v[20:23], v[52:55], v[182:185], v[20:23]
	v_mfma_f32_16x16x32_bf16 v[92:95], v[44:47], v[190:193], v[92:95]
	v_mfma_f32_16x16x32_bf16 v[12:15], v[52:55], v[190:193], v[12:15]
	v_mfma_f32_16x16x32_bf16 v[4:7], v[52:55], v[198:201], v[4:7]
	v_mfma_f32_16x16x32_bf16 v[108:111], v[48:51], v[164:167], v[108:111]
	v_mfma_f32_16x16x32_bf16 v[28:31], v[56:59], v[164:167], v[28:31]
	v_mfma_f32_16x16x32_bf16 v[100:103], v[48:51], v[186:189], v[100:103]
	v_mfma_f32_16x16x32_bf16 v[20:23], v[56:59], v[186:189], v[20:23]
	v_mfma_f32_16x16x32_bf16 v[92:95], v[48:51], v[194:197], v[92:95]
	v_mfma_f32_16x16x32_bf16 v[12:15], v[56:59], v[194:197], v[12:15]
	v_mfma_f32_16x16x32_bf16 v[44:47], v[44:47], v[198:201], v[84:87]
	v_mfma_f32_16x16x32_bf16 v[4:7], v[56:59], v[202:205], v[4:7]
	v_mfma_f32_16x16x32_bf16 v[44:47], v[48:51], v[202:205], v[44:47]
	v_mfma_f32_16x16x32_bf16 v[24:27], v[132:135], v[160:163], v[24:27]
	v_mfma_f32_16x16x32_bf16 v[16:19], v[132:135], v[182:185], v[16:19]
	v_mfma_f32_16x16x32_bf16 v[8:11], v[132:135], v[190:193], v[8:11]
	v_mfma_f32_16x16x32_bf16 v[80:83], v[124:127], v[198:201], v[80:83]
	v_mfma_f32_16x16x32_bf16 v[0:3], v[132:135], v[198:201], v[0:3]
	v_mfma_f32_16x16x32_bf16 v[48:51], v[124:127], v[160:163], v[104:107]
	v_mfma_f32_16x16x32_bf16 v[24:27], v[136:139], v[164:167], v[24:27]
	v_mfma_f32_16x16x32_bf16 v[52:55], v[124:127], v[182:185], v[96:99]
	v_mfma_f32_16x16x32_bf16 v[16:19], v[136:139], v[186:189], v[16:19]
	v_mfma_f32_16x16x32_bf16 v[56:59], v[124:127], v[190:193], v[88:91]
	v_mfma_f32_16x16x32_bf16 v[8:11], v[136:139], v[194:197], v[8:11]
	v_mfma_f32_16x16x32_bf16 v[80:83], v[128:131], v[202:205], v[80:83]
	v_mfma_f32_16x16x32_bf16 v[0:3], v[136:139], v[202:205], v[0:3]
	v_mfma_f32_16x16x32_bf16 v[48:51], v[128:131], v[164:167], v[48:51]
	v_mfma_f32_16x16x32_bf16 v[52:55], v[128:131], v[186:189], v[52:55]
	v_mfma_f32_16x16x32_bf16 v[56:59], v[128:131], v[194:197], v[56:59]
	s_barrier
; #define PG8_STAGE(bufoff, gbase, voff) do { _Pragma("unroll") for (int _i = 0; _i < 2; ++_i) \
;         __builtin_amdgcn_global_load_lds((const unsigned*)((const char*)(gbase) + (voff)[_i]), (LAS unsigned*)(lds + (bufoff) + ldsw + _i * 8192), 16, 0, 0); } while (0)
; #define PG8_LDA(dst, b, h) do { _Pragma("unroll") for (int m = 0; m < 4; ++m) _Pragma("unroll") for (int k = 0; k < 2; ++k) dst[m][k] = *(const LAS bf16x8*)(lds + PG8_SA(b, h) + aoff + m * 2048 + k * 1024); } while (0)
; #define PG8_LDB(dst, b, h) do { _Pragma("unroll") for (int n = 0; n < 2; ++n) _Pragma("unroll") for (int k = 0; k < 2; ++k) dst[n][k] = *(const LAS bf16x8*)(lds + PG8_SB(b, h) + boff + n * 2048 + k * 1024); } while (0)
; #define PG8_MMA(ai, bj, At, Bt) do { __builtin_amdgcn_s_setprio(1); _Pragma("unroll") for (int m = 0; m < 4; ++m) _Pragma("unroll") for (int n = 0; n < 2; ++n) _Pragma("unroll") for (int k = 0; k < 2; ++k) \
;         acc[ai][bj][m][n] = __builtin_amdgcn_mfma_f32_16x16x32_bf16(Bt[n][k], At[m][k], acc[ai][bj][m][n], 0, 0, 0); __builtin_amdgcn_s_setprio(0); } while (0)
; #define PG8_WAIT_V(n) asm volatile("s_waitcnt vmcnt(" #n ")" ::: "memory")
; #define PG8_WAIT_L(n) asm volatile("s_waitcnt lgkmcnt(" #n ")" ::: "memory")
; #define PG8_BAR __builtin_amdgcn_s_barrier()
; #define PG8_SCHED __builtin_amdgcn_sched_barrier(0)
; template <class Epi, class Sched, bool ALIGN_EPI>
; DI void gemm_phase(LAS unsigned char* lds, const Gemm g, const Sched& S, const Epi& E) {
;     ...
;             PG8_LDB(B0, 1, 0); PG8_LDB(B1, 1, 1); PG8_SCHED; PG8_LDA(At, 1, 0); PG8_STAGE(PG8_SA(0, 1), a2 + hstep, voffA);
;             PG8_WAIT_V(8); PG8_WAIT_L(0); PG8_BAR; PG8_MMA(0, 0, At, B0); PG8_MMA(0, 1, At, B1); PG8_BAR; PG8_SCHED;
;             PG8_LDA(At, 1, 1); PG8_STAGE(PG8_SB(1, 0), b3, voffA); PG8_STAGE(PG8_SB(1, 1), b3 + hstep, voffA); PG8_STAGE(PG8_SA(1, 0), a3, voffA);
;             PG8_WAIT_V(8); PG8_WAIT_L(0); PG8_BAR; PG8_MMA(1, 0, At, B0); PG8_MMA(1, 1, At, B1); PG8_BAR; PG8_SCHED;
;         }
;         if constexpr (ALIGN_EPI) { if (wr == 0) PG8_BAR; }
	s_add_i32 s46, 0, 0x18000
	s_add_i32 s47, 0, 0x1c000
	s_add_u32 s34, s34, 0x40000
	s_addc_u32 s35, s35, 0
	s_mov_b32 m0, s33
	s_nop 0
	global_load_lds_dwordx4 v174, s[34:35]
	s_mov_b32 m0, s78
	s_nop 0
	global_load_lds_dwordx4 v176, s[34:35]
	ds_read_b128 v[84:87], v206 offset:32768
	ds_read_b128 v[88:91], v206 offset:33792
	ds_read_b128 v[96:99], v206 offset:34816
	ds_read_b128 v[104:107], v206 offset:35840
	ds_read_b128 v[124:127], v206 offset:49152
	ds_read_b128 v[128:131], v206 offset:50176
	ds_read_b128 v[132:135], v206 offset:51200
	ds_read_b128 v[136:139], v206 offset:52224
	ds_read_b128 v[160:163], v245 offset:32768
	ds_read_b128 v[164:167], v245 offset:33792
	ds_read_b128 v[182:185], v245 offset:34816
	ds_read_b128 v[186:189], v245 offset:35840
	ds_read_b128 v[190:193], v245 offset:36864
	ds_read_b128 v[194:197], v245 offset:37888
	ds_read_b128 v[198:201], v245 offset:38912
	ds_read_b128 v[202:205], v245 offset:39936
	s_waitcnt vmcnt(8)
	s_waitcnt lgkmcnt(0)
	s_barrier
	s_waitcnt lgkmcnt(0)
	v_mfma_f32_16x16x32_bf16 v[156:159], v[84:87], v[160:163], v[156:159]
	v_mfma_f32_16x16x32_bf16 v[76:79], v[96:99], v[160:163], v[76:79]
	v_mfma_f32_16x16x32_bf16 v[148:151], v[84:87], v[182:185], v[148:151]
	v_mfma_f32_16x16x32_bf16 v[68:71], v[96:99], v[182:185], v[68:71]
	v_mfma_f32_16x16x32_bf16 v[140:143], v[84:87], v[190:193], v[140:143]
	v_mfma_f32_16x16x32_bf16 v[60:63], v[96:99], v[190:193], v[60:63]
	v_mfma_f32_16x16x32_bf16 v[116:119], v[84:87], v[198:201], v[116:119]
	v_mfma_f32_16x16x32_bf16 v[36:39], v[96:99], v[198:201], v[36:39]
	v_mfma_f32_16x16x32_bf16 v[156:159], v[88:91], v[164:167], v[156:159]
	v_mfma_f32_16x16x32_bf16 v[76:79], v[104:107], v[164:167], v[76:79]
	v_mfma_f32_16x16x32_bf16 v[148:151], v[88:91], v[186:189], v[148:151]
	v_mfma_f32_16x16x32_bf16 v[68:71], v[104:107], v[186:189], v[68:71]
	v_mfma_f32_16x16x32_bf16 v[140:143], v[88:91], v[194:197], v[140:143]
	v_mfma_f32_16x16x32_bf16 v[60:63], v[104:107], v[194:197], v[60:63]
	v_mfma_f32_16x16x32_bf16 v[116:119], v[88:91], v[202:205], v[116:119]
	v_mfma_f32_16x16x32_bf16 v[36:39], v[104:107], v[202:205], v[36:39]
	v_mfma_f32_16x16x32_bf16 v[152:155], v[124:127], v[160:163], v[152:155]
	v_mfma_f32_16x16x32_bf16 v[72:75], v[132:135], v[160:163], v[72:75]
	v_mfma_f32_16x16x32_bf16 v[144:147], v[124:127], v[182:185], v[144:147]
	v_mfma_f32_16x16x32_bf16 v[64:67], v[132:135], v[182:185], v[64:67]
	v_mfma_f32_16x16x32_bf16 v[120:123], v[124:127], v[190:193], v[120:123]
	v_mfma_f32_16x16x32_bf16 v[40:43], v[132:135], v[190:193], v[40:43]
	v_mfma_f32_16x16x32_bf16 v[112:115], v[124:127], v[198:201], v[112:115]
	v_mfma_f32_16x16x32_bf16 v[32:35], v[132:135], v[198:201], v[32:35]
	v_mfma_f32_16x16x32_bf16 v[152:155], v[128:131], v[164:167], v[152:155]
	v_mfma_f32_16x16x32_bf16 v[72:75], v[136:139], v[164:167], v[72:75]
	v_mfma_f32_16x16x32_bf16 v[144:147], v[128:131], v[186:189], v[144:147]
	v_mfma_f32_16x16x32_bf16 v[64:67], v[136:139], v[186:189], v[64:67]
	v_mfma_f32_16x16x32_bf16 v[120:123], v[128:131], v[194:197], v[120:123]
	v_mfma_f32_16x16x32_bf16 v[40:43], v[136:139], v[194:197], v[40:43]
	v_mfma_f32_16x16x32_bf16 v[112:115], v[128:131], v[202:205], v[112:115]
	v_mfma_f32_16x16x32_bf16 v[32:35], v[136:139], v[202:205], v[32:35]
	s_barrier
	s_add_i32 s34, s46, s92
	s_mov_b32 m0, s34
	s_nop 0
	global_load_lds_dwordx4 v174, s[94:95]
	s_add_i32 m0, s34, 0x2000
	s_add_u32 s30, s30, 0x40080
	s_addc_u32 s31, s31, 0
	s_add_i32 s34, s47, s92
	global_load_lds_dwordx4 v176, s[94:95]
	s_mov_b32 m0, s34
	s_nop 0
	global_load_lds_dwordx4 v174, s[30:31]
	s_add_i32 m0, s34, 0x2000
	s_nop 0
	global_load_lds_dwordx4 v176, s[30:31]
	s_mov_b32 m0, s8
	s_nop 0
	global_load_lds_dwordx4 v174, s[96:97]
	s_mov_b32 m0, s9
	s_nop 0
	global_load_lds_dwordx4 v176, s[96:97]
	ds_read_b128 v[160:163], v245 offset:49152
	ds_read_b128 v[164:167], v245 offset:50176
	ds_read_b128 v[182:185], v245 offset:51200
	ds_read_b128 v[186:189], v245 offset:52224
	ds_read_b128 v[190:193], v245 offset:53248
	ds_read_b128 v[194:197], v245 offset:54272
	ds_read_b128 v[198:201], v245 offset:55296
	ds_read_b128 v[202:205], v245 offset:56320
	s_waitcnt vmcnt(8)
	s_waitcnt lgkmcnt(0)
	s_barrier
	s_waitcnt lgkmcnt(0)
	v_mfma_f32_16x16x32_bf16 v[108:111], v[84:87], v[160:163], v[108:111]
	v_mfma_f32_16x16x32_bf16 v[28:31], v[96:99], v[160:163], v[28:31]
	v_mfma_f32_16x16x32_bf16 v[100:103], v[84:87], v[182:185], v[100:103]
	v_mfma_f32_16x16x32_bf16 v[20:23], v[96:99], v[182:185], v[20:23]
	v_mfma_f32_16x16x32_bf16 v[92:95], v[84:87], v[190:193], v[92:95]
	v_mfma_f32_16x16x32_bf16 v[12:15], v[96:99], v[190:193], v[12:15]
	v_mfma_f32_16x16x32_bf16 v[44:47], v[84:87], v[198:201], v[44:47]
	v_mfma_f32_16x16x32_bf16 v[4:7], v[96:99], v[198:201], v[4:7]
	v_mfma_f32_16x16x32_bf16 v[108:111], v[88:91], v[164:167], v[108:111]
	v_mfma_f32_16x16x32_bf16 v[28:31], v[104:107], v[164:167], v[28:31]
	v_mfma_f32_16x16x32_bf16 v[100:103], v[88:91], v[186:189], v[100:103]
	v_mfma_f32_16x16x32_bf16 v[20:23], v[104:107], v[186:189], v[20:23]
	v_mfma_f32_16x16x32_bf16 v[92:95], v[88:91], v[194:197], v[92:95]
	v_mfma_f32_16x16x32_bf16 v[12:15], v[104:107], v[194:197], v[12:15]
	v_mfma_f32_16x16x32_bf16 v[84:87], v[88:91], v[202:205], v[44:47]
	v_mfma_f32_16x16x32_bf16 v[4:7], v[104:107], v[202:205], v[4:7]
	v_mfma_f32_16x16x32_bf16 v[44:47], v[124:127], v[160:163], v[48:51]
	v_mfma_f32_16x16x32_bf16 v[104:107], v[128:131], v[164:167], v[44:47]
	v_mfma_f32_16x16x32_bf16 v[44:47], v[124:127], v[182:185], v[52:55]
	v_mfma_f32_16x16x32_bf16 v[96:99], v[128:131], v[186:189], v[44:47]
	v_mfma_f32_16x16x32_bf16 v[44:47], v[124:127], v[190:193], v[56:59]
	v_mfma_f32_16x16x32_bf16 v[24:27], v[132:135], v[160:163], v[24:27]
	v_mfma_f32_16x16x32_bf16 v[16:19], v[132:135], v[182:185], v[16:19]
	v_mfma_f32_16x16x32_bf16 v[88:91], v[128:131], v[194:197], v[44:47]
	v_mfma_f32_16x16x32_bf16 v[8:11], v[132:135], v[190:193], v[8:11]
	v_mfma_f32_16x16x32_bf16 v[44:47], v[124:127], v[198:201], v[80:83]
	v_mfma_f32_16x16x32_bf16 v[0:3], v[132:135], v[198:201], v[0:3]
	v_mfma_f32_16x16x32_bf16 v[24:27], v[136:139], v[164:167], v[24:27]
	v_mfma_f32_16x16x32_bf16 v[16:19], v[136:139], v[186:189], v[16:19]
	v_mfma_f32_16x16x32_bf16 v[8:11], v[136:139], v[194:197], v[8:11]
	v_mfma_f32_16x16x32_bf16 v[80:83], v[128:131], v[202:205], v[44:47]
	v_mfma_f32_16x16x32_bf16 v[0:3], v[136:139], v[202:205], v[0:3]
	s_barrier
	s_add_i32 s45, s45, 2
	s_add_u32 s0, s0, 0x100
	s_addc_u32 s1, s1, 0
	s_add_u32 s43, s43, 0x100
	s_addc_u32 s44, s44, 0
	s_cmp_gt_u32 s45, 13
	s_cbranch_scc0 .LBB0_826
	s_and_b64 vcc, exec, s[18:19]
	s_cbranch_vccz .LBB0_829
	s_barrier
